# dropped the conservative vmcnt(0) hipcc placed in front of the accumulator zeroing before each K-loop (template's counted waits already cover the staged tiles)
# baseline (speedup 1.0000x reference)
; template <class Epi, class Sched, bool APERM = false, bool HALFN = false>
; __device__ __forceinline__ void gemm_phase(LAS unsigned char* lds, const int tid_in, const int K, const Sched& S, const Epi& E) {
;     ...
; #pragma unroll
;         for (int a = 0; a < 2; ++a)
; #pragma unroll
;             for (int b = 0; b < 2; ++b)
; #pragma unroll
;                 for (int m = 0; m < 4; ++m)
; #pragma unroll
;                     for (int n = 0; n < 2; ++n) acc[a][b][m][n] = (f32x4){0.f, 0.f, 0.f, 0.f};
;         cur = nxt; cA = nA; cB = nB; ++ui;
.LBB0_681:
	s_add_u32 s45, s18, 0x100
	s_addc_u32 s52, s19, 0
	s_add_u32 s16, s16, 0x80080
	v_mov_b32_e32 v0, 0
	s_addc_u32 s17, s17, 0
	s_mov_b32 s53, -2
	s_waitcnt lgkmcnt(0)
	v_mov_b32_e32 v1, v0
	v_mov_b32_e32 v2, v0
	v_mov_b32_e32 v3, v0
	v_mov_b32_e32 v4, v0
	v_mov_b32_e32 v5, v0
	v_mov_b32_e32 v6, v0
	v_mov_b32_e32 v7, v0
	v_mov_b32_e32 v16, v0
	v_mov_b32_e32 v17, v0
	v_mov_b32_e32 v18, v0
	v_mov_b32_e32 v19, v0
	v_mov_b32_e32 v20, v0
	v_mov_b32_e32 v21, v0
	v_mov_b32_e32 v22, v0
	v_mov_b32_e32 v23, v0
	v_mov_b32_e32 v32, v0
	v_mov_b32_e32 v33, v0
	v_mov_b32_e32 v34, v0
	v_mov_b32_e32 v35, v0
	v_mov_b32_e32 v36, v0
	v_mov_b32_e32 v37, v0
	v_mov_b32_e32 v38, v0
	v_mov_b32_e32 v39, v0
	v_mov_b32_e32 v48, v0
	v_mov_b32_e32 v49, v0
	v_mov_b32_e32 v50, v0
	v_mov_b32_e32 v51, v0
	v_mov_b32_e32 v52, v0
	v_mov_b32_e32 v53, v0
	v_mov_b32_e32 v54, v0
	v_mov_b32_e32 v55, v0
	v_mov_b32_e32 v8, v0
	v_mov_b32_e32 v9, v0
	v_mov_b32_e32 v10, v0
	v_mov_b32_e32 v11, v0
	v_mov_b32_e32 v12, v0
	v_mov_b32_e32 v13, v0
	v_mov_b32_e32 v14, v0
	v_mov_b32_e32 v15, v0
	v_mov_b32_e32 v24, v0
	v_mov_b32_e32 v25, v0
	v_mov_b32_e32 v26, v0
	v_mov_b32_e32 v27, v0
	v_mov_b32_e32 v28, v0
	v_mov_b32_e32 v29, v0
	v_mov_b32_e32 v30, v0
	v_mov_b32_e32 v31, v0
	v_mov_b32_e32 v40, v0
	v_mov_b32_e32 v41, v0
	v_mov_b32_e32 v42, v0
	v_mov_b32_e32 v43, v0
	v_mov_b32_e32 v44, v0
	v_mov_b32_e32 v45, v0
	v_mov_b32_e32 v46, v0
	v_mov_b32_e32 v47, v0
	v_mov_b32_e32 v56, v0
	v_mov_b32_e32 v57, v0
	v_mov_b32_e32 v58, v0
	v_mov_b32_e32 v59, v0
	v_mov_b32_e32 v60, v0
	v_mov_b32_e32 v61, v0
	v_mov_b32_e32 v62, v0
	v_mov_b32_e32 v63, v0
	v_mov_b32_e32 v64, v0
	v_mov_b32_e32 v65, v0
	v_mov_b32_e32 v66, v0
	v_mov_b32_e32 v67, v0
	v_mov_b32_e32 v68, v0
	v_mov_b32_e32 v69, v0
	v_mov_b32_e32 v70, v0
	v_mov_b32_e32 v71, v0
	v_mov_b32_e32 v80, v0
	v_mov_b32_e32 v81, v0
	v_mov_b32_e32 v82, v0
	v_mov_b32_e32 v83, v0
	v_mov_b32_e32 v84, v0
	v_mov_b32_e32 v85, v0
	v_mov_b32_e32 v86, v0
	v_mov_b32_e32 v87, v0
	v_mov_b32_e32 v96, v0
	v_mov_b32_e32 v97, v0
	v_mov_b32_e32 v98, v0
	v_mov_b32_e32 v99, v0
	v_mov_b32_e32 v100, v0
	v_mov_b32_e32 v101, v0
	v_mov_b32_e32 v102, v0
	v_mov_b32_e32 v103, v0
	v_mov_b32_e32 v124, v0
	v_mov_b32_e32 v125, v0
	v_mov_b32_e32 v126, v0
	v_mov_b32_e32 v127, v0
	s_nop 0
	v_mov_b32_e32 v132, v0
	v_mov_b32_e32 v133, v0
	v_mov_b32_e32 v134, v0
	v_mov_b32_e32 v135, v0
	v_mov_b32_e32 v72, v0
	v_mov_b32_e32 v73, v0
	v_mov_b32_e32 v74, v0
	v_mov_b32_e32 v75, v0
	v_mov_b32_e32 v76, v0
	v_mov_b32_e32 v77, v0
	v_mov_b32_e32 v78, v0
	v_mov_b32_e32 v79, v0
	v_mov_b32_e32 v88, v0
	v_mov_b32_e32 v89, v0
	v_mov_b32_e32 v90, v0
	v_mov_b32_e32 v91, v0
	v_mov_b32_e32 v92, v0
	v_mov_b32_e32 v93, v0
	v_mov_b32_e32 v94, v0
	v_mov_b32_e32 v95, v0
	v_mov_b32_e32 v104, v0
	v_mov_b32_e32 v105, v0
	v_mov_b32_e32 v106, v0
	v_mov_b32_e32 v107, v0
	v_mov_b32_e32 v108, v0
	v_mov_b32_e32 v109, v0
	v_mov_b32_e32 v110, v0
	v_mov_b32_e32 v111, v0
	v_mov_b32_e32 v148, v0
	v_mov_b32_e32 v149, v0
	v_mov_b32_e32 v150, v0
	v_mov_b32_e32 v151, v0
	v_mov_b32_e32 v152, v0
	v_mov_b32_e32 v153, v0
	v_mov_b32_e32 v154, v0
	v_mov_b32_e32 v155, v0

; template <class Epi, class Sched, bool APERM = false, bool HALFN = false>
; __device__ __forceinline__ void gemm_phase(LAS unsigned char* lds, const int tid_in, const int K, const Sched& S, const Epi& E) {
;     ...
; #pragma unroll
;         for (int a = 0; a < 2; ++a)
; #pragma unroll
;             for (int b = 0; b < 2; ++b)
; #pragma unroll
;                 for (int m = 0; m < 4; ++m)
; #pragma unroll
;                     for (int n = 0; n < 2; ++n) acc[a][b][m][n] = (f32x4){0.f, 0.f, 0.f, 0.f};
;         cur = nxt; cA = nA; cB = nB; ++ui;
;     __device__ __forceinline__ bool next(int i, AB& u) const {
;         const int Lx = i * G + c; if (Lx >= 128) return false;
;         u.A = (const char*)(ws + WS_HB) + (size_t)(Lx & 31) * 256 * D_ * 2; u.B = (const char*)(ws + WS_W + (size_t)l * SZ_LAYER + OF_WQ) + (size_t)(Lx >> 5) * 128 * D_ * 2; return true;
;     }
.LBB0_765:
	s_mov_b32 s72, s71
	s_add_i32 s71, s71, 1
	s_mov_b64 s[18:19], s[6:7]
	s_mul_i32 s6, s71, s26
	s_mov_b64 s[20:21], s[8:9]
	s_add_i32 s8, s6, s24
	s_cmpk_lt_i32 s8, 0x80
	s_cselect_b64 s[16:17], -1, 0
	s_lshl_b32 s6, s8, 20
	s_and_b32 s6, s6, 0x1f00000
	s_add_u32 s6, s28, s6
	s_addc_u32 s7, s29, 0
	s_ashr_i32 s8, s8, 5
	s_ashr_i32 s9, s8, 31
	s_lshl_b64 s[8:9], s[8:9], 19
	s_add_u32 s8, s30, s8
	s_addc_u32 s9, s31, s9
	s_and_b64 s[22:23], s[16:17], exec
	s_cselect_b32 s74, s9, s21
	s_cselect_b32 s75, s8, s20
	s_cselect_b32 s76, s7, s19
	s_cselect_b32 s77, s6, s18
	s_add_u32 s80, s20, 0x100
	s_addc_u32 s81, s21, 0
	s_add_u32 s18, s18, 0x80080
	v_mov_b32_e32 v0, 0
	s_addc_u32 s19, s19, 0
	s_mov_b32 s86, -2
	v_mov_b32_e32 v1, v0
	v_mov_b32_e32 v2, v0
	v_mov_b32_e32 v3, v0
	v_mov_b32_e32 v4, v0
	v_mov_b32_e32 v5, v0
	v_mov_b32_e32 v6, v0
	v_mov_b32_e32 v7, v0
	v_mov_b32_e32 v8, v0
	v_mov_b32_e32 v9, v0
	v_mov_b32_e32 v10, v0
	v_mov_b32_e32 v11, v0
	v_mov_b32_e32 v12, v0
	v_mov_b32_e32 v13, v0
	v_mov_b32_e32 v14, v0
	v_mov_b32_e32 v15, v0
	v_mov_b32_e32 v16, v0
	v_mov_b32_e32 v17, v0
	v_mov_b32_e32 v18, v0
	v_mov_b32_e32 v19, v0
	v_mov_b32_e32 v20, v0
	v_mov_b32_e32 v21, v0
	v_mov_b32_e32 v22, v0
	v_mov_b32_e32 v23, v0
	v_mov_b32_e32 v24, v0
	v_mov_b32_e32 v25, v0
	v_mov_b32_e32 v26, v0
	v_mov_b32_e32 v27, v0
	v_mov_b32_e32 v28, v0
	v_mov_b32_e32 v29, v0
	v_mov_b32_e32 v30, v0
	v_mov_b32_e32 v31, v0
	v_mov_b32_e32 v32, v0
	v_mov_b32_e32 v33, v0
	v_mov_b32_e32 v34, v0
	v_mov_b32_e32 v35, v0
	v_mov_b32_e32 v36, v0
	v_mov_b32_e32 v37, v0
	v_mov_b32_e32 v38, v0
	v_mov_b32_e32 v39, v0
	v_mov_b32_e32 v40, v0
	v_mov_b32_e32 v41, v0
	v_mov_b32_e32 v42, v0
	v_mov_b32_e32 v43, v0
	v_mov_b32_e32 v44, v0
	v_mov_b32_e32 v45, v0
	v_mov_b32_e32 v46, v0
	v_mov_b32_e32 v47, v0
	v_mov_b32_e32 v48, v0
	v_mov_b32_e32 v49, v0
	v_mov_b32_e32 v50, v0
	v_mov_b32_e32 v51, v0
	v_mov_b32_e32 v52, v0
	v_mov_b32_e32 v53, v0
	v_mov_b32_e32 v54, v0
	v_mov_b32_e32 v55, v0
	v_mov_b32_e32 v56, v0
	v_mov_b32_e32 v57, v0
	v_mov_b32_e32 v58, v0
	v_mov_b32_e32 v59, v0
	v_mov_b32_e32 v60, v0
	v_mov_b32_e32 v61, v0
	v_mov_b32_e32 v62, v0
	v_mov_b32_e32 v63, v0
	s_nop 0

; template <class Epi, class Sched, bool APERM = false, bool HALFN = false>
; __device__ __forceinline__ void gemm_phase(LAS unsigned char* lds, const int tid_in, const int K, const Sched& S, const Epi& E) {
;     ...
; #pragma unroll
;         for (int a = 0; a < 2; ++a)
; #pragma unroll
;             for (int b = 0; b < 2; ++b)
; #pragma unroll
;                 for (int m = 0; m < 4; ++m)
; #pragma unroll
;                     for (int n = 0; n < 2; ++n) acc[a][b][m][n] = (f32x4){0.f, 0.f, 0.f, 0.f};
;         cur = nxt; cA = nA; cB = nB; ++ui;
.LBB0_805:
	s_add_u32 s45, s18, 0x100
	s_addc_u32 s52, s19, 0
	s_add_u32 s16, s16, 0x20080
	v_mov_b32_e32 v0, 0
	s_addc_u32 s17, s17, 0
	s_mov_b32 s53, -2
	s_waitcnt lgkmcnt(0)
	v_mov_b32_e32 v1, v0
	v_mov_b32_e32 v2, v0
	v_mov_b32_e32 v3, v0
	v_mov_b32_e32 v4, v0
	v_mov_b32_e32 v5, v0
	v_mov_b32_e32 v6, v0
	v_mov_b32_e32 v7, v0
	v_mov_b32_e32 v16, v0
	v_mov_b32_e32 v17, v0
	v_mov_b32_e32 v18, v0
	v_mov_b32_e32 v19, v0
	v_mov_b32_e32 v20, v0
	v_mov_b32_e32 v21, v0
	v_mov_b32_e32 v22, v0
	v_mov_b32_e32 v23, v0
	v_mov_b32_e32 v32, v0
	v_mov_b32_e32 v33, v0
	v_mov_b32_e32 v34, v0
	v_mov_b32_e32 v35, v0
	v_mov_b32_e32 v36, v0
	v_mov_b32_e32 v37, v0
	v_mov_b32_e32 v38, v0
	v_mov_b32_e32 v39, v0
	v_mov_b32_e32 v48, v0
	v_mov_b32_e32 v49, v0
	v_mov_b32_e32 v50, v0
	v_mov_b32_e32 v51, v0
	v_mov_b32_e32 v52, v0
	v_mov_b32_e32 v53, v0
	v_mov_b32_e32 v54, v0
	v_mov_b32_e32 v55, v0
	v_mov_b32_e32 v8, v0
	v_mov_b32_e32 v9, v0
	v_mov_b32_e32 v10, v0
	v_mov_b32_e32 v11, v0
	v_mov_b32_e32 v12, v0
	v_mov_b32_e32 v13, v0
	v_mov_b32_e32 v14, v0
	v_mov_b32_e32 v15, v0
	v_mov_b32_e32 v24, v0
	v_mov_b32_e32 v25, v0
	v_mov_b32_e32 v26, v0
	v_mov_b32_e32 v27, v0
	v_mov_b32_e32 v28, v0
	v_mov_b32_e32 v29, v0
	v_mov_b32_e32 v30, v0
	v_mov_b32_e32 v31, v0
	v_mov_b32_e32 v40, v0
	v_mov_b32_e32 v41, v0
	v_mov_b32_e32 v42, v0
	v_mov_b32_e32 v43, v0
	v_mov_b32_e32 v44, v0
	v_mov_b32_e32 v45, v0
	v_mov_b32_e32 v46, v0
	v_mov_b32_e32 v47, v0
	v_mov_b32_e32 v56, v0
	v_mov_b32_e32 v57, v0
	v_mov_b32_e32 v58, v0
	v_mov_b32_e32 v59, v0
	v_mov_b32_e32 v60, v0
	v_mov_b32_e32 v61, v0
	v_mov_b32_e32 v62, v0
	v_mov_b32_e32 v63, v0
	v_mov_b32_e32 v64, v0
	v_mov_b32_e32 v65, v0
	v_mov_b32_e32 v66, v0
	v_mov_b32_e32 v67, v0
	v_mov_b32_e32 v68, v0
	v_mov_b32_e32 v69, v0
	v_mov_b32_e32 v70, v0
	v_mov_b32_e32 v71, v0
	v_mov_b32_e32 v80, v0
	v_mov_b32_e32 v81, v0
	v_mov_b32_e32 v82, v0
	v_mov_b32_e32 v83, v0
	v_mov_b32_e32 v84, v0
	v_mov_b32_e32 v85, v0
	v_mov_b32_e32 v86, v0
	v_mov_b32_e32 v87, v0
	v_mov_b32_e32 v96, v0
	v_mov_b32_e32 v97, v0
	v_mov_b32_e32 v98, v0
	v_mov_b32_e32 v99, v0
	v_mov_b32_e32 v100, v0
	v_mov_b32_e32 v101, v0
	v_mov_b32_e32 v102, v0
	v_mov_b32_e32 v103, v0
	v_mov_b32_e32 v124, v0
	v_mov_b32_e32 v125, v0
	v_mov_b32_e32 v126, v0
	v_mov_b32_e32 v127, v0
	s_nop 0
	v_mov_b32_e32 v132, v0
	v_mov_b32_e32 v133, v0
	v_mov_b32_e32 v134, v0
	v_mov_b32_e32 v135, v0
	v_mov_b32_e32 v72, v0
	v_mov_b32_e32 v73, v0
	v_mov_b32_e32 v74, v0
	v_mov_b32_e32 v75, v0
	v_mov_b32_e32 v76, v0
	v_mov_b32_e32 v77, v0
	v_mov_b32_e32 v78, v0
	v_mov_b32_e32 v79, v0
	v_mov_b32_e32 v88, v0
	v_mov_b32_e32 v89, v0
	v_mov_b32_e32 v90, v0
	v_mov_b32_e32 v91, v0
	v_mov_b32_e32 v92, v0
	v_mov_b32_e32 v93, v0
	v_mov_b32_e32 v94, v0
	v_mov_b32_e32 v95, v0
	v_mov_b32_e32 v104, v0
	v_mov_b32_e32 v105, v0
	v_mov_b32_e32 v106, v0
	v_mov_b32_e32 v107, v0
	v_mov_b32_e32 v108, v0
	v_mov_b32_e32 v109, v0
	v_mov_b32_e32 v110, v0
	v_mov_b32_e32 v111, v0
	v_mov_b32_e32 v148, v0
	v_mov_b32_e32 v149, v0
	v_mov_b32_e32 v150, v0
	v_mov_b32_e32 v151, v0
	v_mov_b32_e32 v152, v0
	v_mov_b32_e32 v153, v0
	v_mov_b32_e32 v154, v0
	v_mov_b32_e32 v155, v0

; template <class Epi, class Sched, bool APERM = false, bool HALFN = false>
; __device__ __forceinline__ void gemm_phase(LAS unsigned char* lds, const int tid_in, const int K, const Sched& S, const Epi& E) {
;     ...
; #pragma unroll
;         for (int a = 0; a < 2; ++a)
; #pragma unroll
;             for (int b = 0; b < 2; ++b)
; #pragma unroll
;                 for (int m = 0; m < 4; ++m)
; #pragma unroll
;                     for (int n = 0; n < 2; ++n) acc[a][b][m][n] = (f32x4){0.f, 0.f, 0.f, 0.f};
;         cur = nxt; cA = nA; cB = nB; ++ui;
;     __device__ __forceinline__ void operator()(const f32x4 (&acc)[2][2][4][2], const CU2& u, int wr, int wc, int fr_, int fq_) const {
;     ...
;             const float* wp = cw + 128 * u.pn + cl + 4 * n; const float* bp = cb + 128 * u.pn + cl + 4 * n;
;             const f32x4 g0 = *(const f32x4*)wp, g1 = *(const f32x4*)(wp + 2 * FF_), g2 = *(const f32x4*)(wp + 4 * FF_), gb = *(const f32x4*)bp;
;             const f32x4 v0 = *(const f32x4*)(wp + FF_), v1 = *(const f32x4*)(wp + 3 * FF_), v2 = *(const f32x4*)(wp + 5 * FF_), vb = *(const f32x4*)(bp + FF_);
.LBB0_901:
	s_add_u32 s11, s4, 0x100
	v_mov_b32_e32 v44, 0
	s_addc_u32 s12, s5, 0
	s_mov_b32 s13, -2
	v_mov_b32_e32 v45, v44
	v_mov_b32_e32 v46, v44
	v_mov_b32_e32 v47, v44
	s_waitcnt lgkmcnt(0)
	v_mov_b32_e32 v76, v44
	v_mov_b32_e32 v77, v44
	v_mov_b32_e32 v78, v44
	v_mov_b32_e32 v79, v44
	v_mov_b32_e32 v54, v44
	v_mov_b32_e32 v55, v44
	v_mov_b32_e32 v56, v44
	v_mov_b32_e32 v57, v44
	v_mov_b32_e32 v84, v44
	v_mov_b32_e32 v85, v44
	v_mov_b32_e32 v86, v44
	v_mov_b32_e32 v87, v44
	v_mov_b32_e32 v0, v44
	v_mov_b32_e32 v1, v44
	v_mov_b32_e32 v2, v44
	v_mov_b32_e32 v3, v44
	v_mov_b32_e32 v88, v44
	v_mov_b32_e32 v89, v44
	v_mov_b32_e32 v90, v44
	v_mov_b32_e32 v91, v44
	v_mov_b32_e32 v8, v44
	v_mov_b32_e32 v9, v44
	v_mov_b32_e32 v10, v44
	v_mov_b32_e32 v11, v44
	v_mov_b32_e32 v96, v44
	v_mov_b32_e32 v97, v44
	v_mov_b32_e32 v98, v44
	v_mov_b32_e32 v99, v44
	v_mov_b32_e32 v68, v44
	v_mov_b32_e32 v69, v44
	v_mov_b32_e32 v70, v44
	v_mov_b32_e32 v71, v44
	v_mov_b32_e32 v80, v44
	v_mov_b32_e32 v81, v44
	v_mov_b32_e32 v82, v44
	v_mov_b32_e32 v83, v44
	v_mov_b32_e32 v72, v44
	v_mov_b32_e32 v73, v44
	v_mov_b32_e32 v74, v44
	v_mov_b32_e32 v75, v44
	v_mov_b32_e32 v48, v44
	v_mov_b32_e32 v49, v44
	v_mov_b32_e32 v50, v44
	v_mov_b32_e32 v51, v44
	v_mov_b32_e32 v4, v44
	v_mov_b32_e32 v5, v44
	v_mov_b32_e32 v6, v44
	v_mov_b32_e32 v7, v44
	v_mov_b32_e32 v92, v44
	v_mov_b32_e32 v93, v44
	v_mov_b32_e32 v94, v44
	v_mov_b32_e32 v95, v44
	v_mov_b32_e32 v12, v44
	v_mov_b32_e32 v13, v44
	v_mov_b32_e32 v14, v44
	v_mov_b32_e32 v15, v44
	v_mov_b32_e32 v100, v44
	v_mov_b32_e32 v101, v44
	v_mov_b32_e32 v102, v44
	v_mov_b32_e32 v103, v44
	v_mov_b32_e32 v16, v44
	v_mov_b32_e32 v17, v44
	v_mov_b32_e32 v18, v44
	v_mov_b32_e32 v19, v44
	v_mov_b32_e32 v104, v44
	v_mov_b32_e32 v105, v44
	v_mov_b32_e32 v106, v44
	v_mov_b32_e32 v107, v44
	v_mov_b32_e32 v24, v44
	v_mov_b32_e32 v25, v44
	v_mov_b32_e32 v26, v44
	v_mov_b32_e32 v27, v44
	s_nop 0
	v_mov_b32_e32 v112, v44
	v_mov_b32_e32 v113, v44
	v_mov_b32_e32 v114, v44
	v_mov_b32_e32 v115, v44
	v_mov_b32_e32 v32, v44
	v_mov_b32_e32 v33, v44
	v_mov_b32_e32 v34, v44
	v_mov_b32_e32 v35, v44
	v_mov_b32_e32 v120, v44
	v_mov_b32_e32 v121, v44
	v_mov_b32_e32 v122, v44
	v_mov_b32_e32 v123, v44
	v_mov_b32_e32 v40, v44
	v_mov_b32_e32 v41, v44
	v_mov_b32_e32 v42, v44
	v_mov_b32_e32 v43, v44
	v_mov_b32_e32 v144, v44
	v_mov_b32_e32 v145, v44
	v_mov_b32_e32 v146, v44
	v_mov_b32_e32 v147, v44
	v_mov_b32_e32 v20, v44
	v_mov_b32_e32 v21, v44
	v_mov_b32_e32 v22, v44
	v_mov_b32_e32 v23, v44
	v_mov_b32_e32 v108, v44
	v_mov_b32_e32 v109, v44
	v_mov_b32_e32 v110, v44
	v_mov_b32_e32 v111, v44
	v_mov_b32_e32 v28, v44
	v_mov_b32_e32 v29, v44
	v_mov_b32_e32 v30, v44
	v_mov_b32_e32 v31, v44
	v_mov_b32_e32 v116, v44
	v_mov_b32_e32 v117, v44
	v_mov_b32_e32 v118, v44
	v_mov_b32_e32 v119, v44
	v_mov_b32_e32 v36, v44
	v_mov_b32_e32 v37, v44
	v_mov_b32_e32 v38, v44
	v_mov_b32_e32 v39, v44
	v_mov_b32_e32 v124, v44
	v_mov_b32_e32 v125, v44
	v_mov_b32_e32 v126, v44
	v_mov_b32_e32 v127, v44
	v_mov_b32_e32 v58, v44
	v_mov_b32_e32 v59, v44
	v_mov_b32_e32 v60, v44
	v_mov_b32_e32 v61, v44
	v_mov_b32_e32 v148, v44
	v_mov_b32_e32 v149, v44
	v_mov_b32_e32 v150, v44
	v_mov_b32_e32 v151, v44
	v_readfirstlane_b32 s26, v234
	s_and_b32 s27, s10, 1
	s_mulk_i32 s27, 0x1800
	s_lshr_b32 s26, s26, 6
	s_add_i32 s27, s27, 0x20800
	s_cmp_gt_u32 s26, 5
	s_cbranch_scc1 .Lpf_done
	s_cmp_gt_u32 s26, 3
	s_cbranch_scc1 .Lpf_ssq
	s_sub_u32 s28, s4, s95
	s_lshr_b32 s28, s28, 20
	s_lshl_b32 s28, s28, 9
	s_lshr_b32 s29, s26, 1
	s_mulk_i32 s29, 0x5800
	s_add_i32 s28, s28, s29
	s_bitcmp1_b32 s26, 0
	s_cselect_b32 s29, 0x16000, 0
	s_cselect_b32 s30, s74, s76
	s_cselect_b32 s31, s75, s77
	s_cselect_b32 s53, 0, 0xb000
	s_add_i32 s29, s29, s28
	s_add_i32 s53, s53, s28
	s_add_u32 s28, s76, s29
	s_addc_u32 s29, s77, 0
	s_add_u32 s30, s30, s53
	s_addc_u32 s31, s31, 0
	v_and_b32_e32 v236, 31, v235
	v_lshlrev_b32_e32 v236, 4, v236
	v_mov_b32_e32 v237, 0
	v_cmp_gt_u32_e32 vcc, 32, v235
	v_mov_b32_e32 v248, s30
	v_mov_b32_e32 v249, s31
	v_mov_b32_e32 v250, s28
	v_mov_b32_e32 v251, s29
	s_nop 0
	v_cndmask_b32_e32 v248, v248, v250, vcc
	v_cndmask_b32_e32 v249, v249, v251, vcc
	v_lshl_add_u64 v[236:237], v[248:249], 0, v[236:237]
	s_lshl_b32 s28, s26, 10
	s_add_i32 m0, s27, s28
	s_nop 0
	global_load_lds_dwordx4 v[236:237], off
	s_branch .Lpf_done

; template <class Epi, class Sched, bool APERM = false, bool HALFN = false>
; __device__ __forceinline__ void gemm_phase(LAS unsigned char* lds, const int tid_in, const int K, const Sched& S, const Epi& E) {
;     ...
; #pragma unroll
;         for (int a = 0; a < 2; ++a)
; #pragma unroll
;             for (int b = 0; b < 2; ++b)
; #pragma unroll
;                 for (int m = 0; m < 4; ++m)
; #pragma unroll
;                     for (int n = 0; n < 2; ++n) acc[a][b][m][n] = (f32x4){0.f, 0.f, 0.f, 0.f};
;         cur = nxt; cA = nA; cB = nB; ++ui;
.LBB0_1032:
	s_add_u32 s53, s18, 0x100
	v_mov_b32_e32 v0, 0
	s_addc_u32 s57, s19, 0
	s_mov_b32 s70, -2
	s_waitcnt lgkmcnt(0)
	v_mov_b32_e32 v1, v0
	v_mov_b32_e32 v2, v0
	v_mov_b32_e32 v3, v0
	v_mov_b32_e32 v4, v0
	v_mov_b32_e32 v5, v0
	v_mov_b32_e32 v6, v0
	v_mov_b32_e32 v7, v0
	v_mov_b32_e32 v16, v0
	v_mov_b32_e32 v17, v0
	v_mov_b32_e32 v18, v0
	v_mov_b32_e32 v19, v0
	v_mov_b32_e32 v20, v0
	v_mov_b32_e32 v21, v0
	v_mov_b32_e32 v22, v0
	v_mov_b32_e32 v23, v0
	v_mov_b32_e32 v32, v0
	v_mov_b32_e32 v33, v0
	v_mov_b32_e32 v34, v0
	v_mov_b32_e32 v35, v0
	v_mov_b32_e32 v36, v0
	v_mov_b32_e32 v37, v0
	v_mov_b32_e32 v38, v0
	v_mov_b32_e32 v39, v0
	v_mov_b32_e32 v48, v0
	v_mov_b32_e32 v49, v0
	v_mov_b32_e32 v50, v0
	v_mov_b32_e32 v51, v0
	v_mov_b32_e32 v52, v0
	v_mov_b32_e32 v53, v0
	v_mov_b32_e32 v54, v0
	v_mov_b32_e32 v55, v0
	v_mov_b32_e32 v8, v0
	v_mov_b32_e32 v9, v0
	v_mov_b32_e32 v10, v0
	v_mov_b32_e32 v11, v0
	v_mov_b32_e32 v12, v0
	v_mov_b32_e32 v13, v0
	v_mov_b32_e32 v14, v0
	v_mov_b32_e32 v15, v0
	v_mov_b32_e32 v24, v0
	v_mov_b32_e32 v25, v0
	v_mov_b32_e32 v26, v0
	v_mov_b32_e32 v27, v0
	v_mov_b32_e32 v28, v0
	v_mov_b32_e32 v29, v0
	v_mov_b32_e32 v30, v0
	v_mov_b32_e32 v31, v0
	v_mov_b32_e32 v40, v0
	v_mov_b32_e32 v41, v0
	v_mov_b32_e32 v42, v0
	v_mov_b32_e32 v43, v0
	v_mov_b32_e32 v44, v0
	v_mov_b32_e32 v45, v0
	v_mov_b32_e32 v46, v0
	v_mov_b32_e32 v47, v0
	v_mov_b32_e32 v56, v0
	v_mov_b32_e32 v57, v0
	v_mov_b32_e32 v58, v0
	v_mov_b32_e32 v59, v0
	v_mov_b32_e32 v60, v0
	v_mov_b32_e32 v61, v0
	v_mov_b32_e32 v62, v0
	v_mov_b32_e32 v63, v0
	v_mov_b32_e32 v64, v0
	v_mov_b32_e32 v65, v0
	v_mov_b32_e32 v66, v0
	v_mov_b32_e32 v67, v0
	v_mov_b32_e32 v68, v0
	v_mov_b32_e32 v69, v0
	v_mov_b32_e32 v70, v0
	v_mov_b32_e32 v71, v0
	s_nop 0
	v_mov_b32_e32 v80, v0
	v_mov_b32_e32 v81, v0
	v_mov_b32_e32 v82, v0
	v_mov_b32_e32 v83, v0
	v_mov_b32_e32 v84, v0
	v_mov_b32_e32 v85, v0
	v_mov_b32_e32 v86, v0
	v_mov_b32_e32 v87, v0
	v_mov_b32_e32 v96, v0
	v_mov_b32_e32 v97, v0
	v_mov_b32_e32 v98, v0
	v_mov_b32_e32 v99, v0
	v_mov_b32_e32 v100, v0
	v_mov_b32_e32 v101, v0
	v_mov_b32_e32 v102, v0
	v_mov_b32_e32 v103, v0
	v_mov_b32_e32 v124, v0
	v_mov_b32_e32 v125, v0
	v_mov_b32_e32 v126, v0
	v_mov_b32_e32 v127, v0
	v_mov_b32_e32 v132, v0
	v_mov_b32_e32 v133, v0
	v_mov_b32_e32 v134, v0
	v_mov_b32_e32 v135, v0
	v_mov_b32_e32 v72, v0
	v_mov_b32_e32 v73, v0
	v_mov_b32_e32 v74, v0
	v_mov_b32_e32 v75, v0
	v_mov_b32_e32 v76, v0
	v_mov_b32_e32 v77, v0
	v_mov_b32_e32 v78, v0
	v_mov_b32_e32 v79, v0
	v_mov_b32_e32 v88, v0
	v_mov_b32_e32 v89, v0
	v_mov_b32_e32 v90, v0
	v_mov_b32_e32 v91, v0
	v_mov_b32_e32 v92, v0
	v_mov_b32_e32 v93, v0
	v_mov_b32_e32 v94, v0
	v_mov_b32_e32 v95, v0
	v_mov_b32_e32 v104, v0
	v_mov_b32_e32 v105, v0
	v_mov_b32_e32 v106, v0
	v_mov_b32_e32 v107, v0
	v_mov_b32_e32 v108, v0
	v_mov_b32_e32 v109, v0
	v_mov_b32_e32 v110, v0
	v_mov_b32_e32 v111, v0
	v_mov_b32_e32 v148, v0
	v_mov_b32_e32 v149, v0
	v_mov_b32_e32 v150, v0
	v_mov_b32_e32 v151, v0
	v_mov_b32_e32 v152, v0
	v_mov_b32_e32 v153, v0
	v_mov_b32_e32 v154, v0
	v_mov_b32_e32 v155, v0
